# XCD start offset doubled (x * ~6us)
# baseline (speedup 1.0000x reference)
; __device__ __forceinline__ unsigned xb_ld(unsigned* p)              { return __hip_atomic_load(p, __ATOMIC_RELAXED, __HIP_MEMORY_SCOPE_AGENT); }
; __global__ void __launch_bounds__(512, 2) fwd_megakernel(Args a) {
;     ...
;             if (s == 0) {
;                 if (threadIdx.x == 0) { unsigned ok = (G == 256) ? 1u : 0u;
;                     for (unsigned j = 0; j < 16; ++j) { const unsigned c = xb_ld(&bar.bar[XB_XCNT(j)]); ok &= (j < 8) ? (c == 32u) : (c == 0u); }
;                     bst[3] = ok; }
;                 __syncthreads();
;                 grp = __builtin_amdgcn_readfirstlane((int)bst[3]);
;                 if (grp) vb = __builtin_amdgcn_readfirstlane((int)bst[2]) * 8 + (int)bar.x;
.Lstag_loop:
	s_sleep 100
	s_sleep 100
	s_sub_u32 s2, s2, 1
	s_cmp_lg_u32 s2, 0
	s_cbranch_scc1 .Lstag_loop
